# v49: GEMM tile prologues (P1 P8 P3 P4): stage-1 loads issued before the row-scale block, no vmcnt(0) drain before acc zeroing
# baseline (speedup 1.0000x reference)
.LBB0_532:
	v_mov_b32_e32 v79, 0
	s_and_b64 vcc, exec, s[16:17]
	v_mov_b32_e32 v78, 0
	v_mov_b32_e32 v77, 0
	v_mov_b32_e32 v76, 0
	v_mov_b32_e32 v75, 0
	v_mov_b32_e32 v74, 0
	v_mov_b32_e32 v73, 0
	v_mov_b32_e32 v72, 0
	v_mov_b32_e32 v71, 0
	v_mov_b32_e32 v70, 0
	v_mov_b32_e32 v69, 0
	v_mov_b32_e32 v68, 0
	v_mov_b32_e32 v67, 0
	v_mov_b32_e32 v66, 0
	v_mov_b32_e32 v65, 0
	v_mov_b32_e32 v64, 0
	v_mov_b32_e32 v95, 0
	v_mov_b32_e32 v94, 0
	v_mov_b32_e32 v93, 0
	v_mov_b32_e32 v92, 0
	v_mov_b32_e32 v91, 0
	v_mov_b32_e32 v90, 0
	v_mov_b32_e32 v89, 0
	v_mov_b32_e32 v88, 0
	v_mov_b32_e32 v87, 0
	v_mov_b32_e32 v86, 0
	v_mov_b32_e32 v85, 0
	v_mov_b32_e32 v84, 0
	v_mov_b32_e32 v83, 0
	v_mov_b32_e32 v82, 0
	v_mov_b32_e32 v81, 0
	v_mov_b32_e32 v80, 0
	v_mov_b32_e32 v31, 0
	v_mov_b32_e32 v30, 0
	v_mov_b32_e32 v29, 0
	v_mov_b32_e32 v28, 0
	v_mov_b32_e32 v27, 0
	v_mov_b32_e32 v26, 0
	v_mov_b32_e32 v25, 0
	v_mov_b32_e32 v24, 0
	v_mov_b32_e32 v23, 0
	v_mov_b32_e32 v22, 0
	v_mov_b32_e32 v21, 0
	v_mov_b32_e32 v20, 0
	v_mov_b32_e32 v19, 0
	v_mov_b32_e32 v18, 0
	v_mov_b32_e32 v17, 0
	v_mov_b32_e32 v16, 0
	v_mov_b32_e32 v15, 0
	v_mov_b32_e32 v14, 0
	v_mov_b32_e32 v13, 0
	v_mov_b32_e32 v12, 0
	v_mov_b32_e32 v11, 0
	v_mov_b32_e32 v10, 0
	v_mov_b32_e32 v9, 0
	v_mov_b32_e32 v8, 0
	v_mov_b32_e32 v7, 0
	v_mov_b32_e32 v6, 0
	v_mov_b32_e32 v5, 0
	v_mov_b32_e32 v4, 0
	v_mov_b32_e32 v3, 0
	v_mov_b32_e32 v2, 0
	v_mov_b32_e32 v1, 0
	v_mov_b32_e32 v0, 0
	s_cbranch_vccz .LBB0_513
	s_cmp_gt_i32 s28, 1
	s_cselect_b32 s7, 0x80, 0
	s_add_u32 s14, s14, s7
	s_addc_u32 s15, s15, 0
	v_lshl_add_u64 v[240:241], s[14:15], 0, v[192:193]
	s_add_u32 s12, s12, s7
	v_lshl_add_u64 v[242:243], s[14:15], 0, v[194:195]
	global_load_dwordx4 v[128:131], v[240:241], off
	global_load_dwordx4 v[132:135], v[242:243], off
	v_lshl_add_u64 v[240:241], s[14:15], 0, v[196:197]
	s_addc_u32 s13, s13, 0
	v_lshl_add_u64 v[242:243], s[14:15], 0, v[198:199]
	global_load_dwordx4 v[140:143], v[240:241], off
	global_load_dwordx4 v[136:139], v[242:243], off
	v_lshl_add_u64 v[240:241], s[12:13], 0, v[192:193]
	v_lshl_add_u64 v[242:243], s[12:13], 0, v[194:195]
	global_load_dwordx4 v[148:151], v[240:241], off
	global_load_dwordx4 v[144:147], v[242:243], off
	v_lshl_add_u64 v[240:241], s[12:13], 0, v[196:197]
	v_lshl_add_u64 v[242:243], s[12:13], 0, v[198:199]
	global_load_dwordx4 v[152:155], v[240:241], off
	global_load_dwordx4 v[156:159], v[242:243], off
	s_and_saveexec_b64 s[16:17], s[2:3]
	s_cbranch_execz .LBB0_535
	v_or_b32_e32 v0, s6, v208
	v_ashrrev_i32_e32 v1, 31, v0
	v_lshlrev_b64 v[0:1], 6, v[0:1]
	v_lshl_add_u64 v[12:13], s[0:1], 0, v[0:1]
	global_load_dwordx4 v[0:3], v[12:13], off
	global_load_dwordx4 v[4:7], v[12:13], off offset:16
	global_load_dwordx4 v[8:11], v[12:13], off offset:32
	s_nop 0
	global_load_dwordx4 v[12:15], v[12:13], off offset:48
	s_waitcnt vmcnt(3)
	v_mov_b32_e32 v16, v1
	v_mov_b32_e32 v17, v2
	s_waitcnt vmcnt(2)
	v_mov_b32_e32 v18, v5
	v_mov_b32_e32 v19, v6
	v_mov_b32_e32 v1, v3
	v_mov_b32_e32 v5, v7
	s_waitcnt vmcnt(1)
	v_mov_b32_e32 v2, v9
	v_mov_b32_e32 v6, v11
	v_pk_add_f32 v[0:1], v[16:17], v[0:1]
	v_pk_add_f32 v[4:5], v[18:19], v[4:5]
	v_pk_add_f32 v[2:3], v[8:9], v[2:3]
	v_pk_add_f32 v[6:7], v[10:11], v[6:7]
	v_pk_add_f32 v[0:1], v[0:1], v[0:1] op_sel:[0,1] op_sel_hi:[1,0]
	v_pk_add_f32 v[4:5], v[4:5], v[4:5] op_sel:[0,1] op_sel_hi:[1,0]
	s_waitcnt vmcnt(0)
	v_mov_b32_e32 v3, v14
	v_mov_b32_e32 v7, v15
	v_mov_b32_e32 v1, v12
	v_mov_b32_e32 v5, v13
	v_pk_add_f32 v[2:3], v[2:3], v[6:7]
	v_pk_add_f32 v[0:1], v[0:1], v[4:5]
	s_nop 0
	v_pk_add_f32 v[0:1], v[0:1], v[2:3]
	s_nop 0
	v_add_f32_e32 v0, v0, v1
	v_fmamk_f32 v0, v0, 0x3a800000, v202
	v_mul_f32_e32 v1, 0x4b800000, v0
	v_cmp_gt_f32_e32 vcc, s23, v0
	s_nop 1
	v_cndmask_b32_e32 v0, v0, v1, vcc
	v_rsq_f32_e32 v0, v0
	s_nop 0
	v_mul_f32_e32 v1, 0x45800000, v0
	v_cndmask_b32_e32 v0, v0, v1, vcc
	ds_write_b32 v201, v0
.LBB0_535:
	s_or_b64 exec, exec, s[16:17]
	v_mul_lo_u32 v0, v203, s24
	v_lshl_add_u32 v203, v210, 1, v0
	v_or_b32_e32 v0, v207, v205
	v_lshlrev_b32_e32 v1, 3, v206
	v_lshl_or_b32 v2, v204, 6, v205
	s_waitcnt vmcnt(8)
	ds_write_b128 v203, v[160:163]
	ds_write_b128 v203, v[180:183] offset:9216
	ds_write_b128 v203, v[184:187] offset:18432
	ds_write_b128 v203, v[188:191] offset:27648
	ds_write_b128 v203, v[164:167] offset:36864
	ds_write_b128 v203, v[168:171] offset:46080
	ds_write_b128 v203, v[172:175] offset:55296
	ds_write_b128 v203, v[176:179] offset:64512
	s_mov_b32 s7, 0
	s_mov_b32 s12, 0
	s_cmp_lt_i32 s28, 3
	v_mul_lo_u32 v176, v0, s24
	v_mul_u32_u24_e32 v177, 0x90, v2
	v_lshlrev_b32_e32 v178, 1, v1
	s_waitcnt lgkmcnt(0)
	s_barrier
	s_cbranch_scc1 .LBB0_539
	s_add_i32 s7, s28, -2
	s_add_u32 s8, s8, 0x7dbbb00
	s_addc_u32 s9, s9, 0
	v_lshl_add_u64 v[160:161], s[8:9], 0, v[192:193]
	v_lshl_add_u64 v[162:163], s[8:9], 0, v[194:195]
	v_lshl_add_u64 v[164:165], s[8:9], 0, v[196:197]
	v_lshl_add_u64 v[166:167], s[8:9], 0, v[198:199]
	s_add_u32 s8, s10, 0x6d3bb00
	s_addc_u32 s9, s11, 0
	v_mov_b32_e32 v0, 0
	v_lshl_add_u64 v[168:169], s[8:9], 0, v[192:193]
	v_lshl_add_u64 v[170:171], s[8:9], 0, v[194:195]
	v_lshl_add_u64 v[172:173], s[8:9], 0, v[196:197]
	v_lshl_add_u64 v[174:175], s[8:9], 0, v[198:199]
	s_mov_b64 s[8:9], s[90:91]
	v_mov_b32_e32 v1, v0
	v_mov_b32_e32 v2, v0
	v_mov_b32_e32 v3, v0
	v_mov_b32_e32 v4, v0
	v_mov_b32_e32 v5, v0
	v_mov_b32_e32 v6, v0
	v_mov_b32_e32 v7, v0
	v_mov_b32_e32 v8, v0
	v_mov_b32_e32 v9, v0
	v_mov_b32_e32 v10, v0
	v_mov_b32_e32 v11, v0
	v_mov_b32_e32 v12, v0
	v_mov_b32_e32 v13, v0
	v_mov_b32_e32 v14, v0
	v_mov_b32_e32 v15, v0
	v_mov_b32_e32 v16, v0
	v_mov_b32_e32 v17, v0
	v_mov_b32_e32 v18, v0
	v_mov_b32_e32 v19, v0
	v_mov_b32_e32 v20, v0
	v_mov_b32_e32 v21, v0
	v_mov_b32_e32 v22, v0
	v_mov_b32_e32 v23, v0
	v_mov_b32_e32 v24, v0
	v_mov_b32_e32 v25, v0
	v_mov_b32_e32 v26, v0
	v_mov_b32_e32 v27, v0
	v_mov_b32_e32 v28, v0
	v_mov_b32_e32 v29, v0
	v_mov_b32_e32 v30, v0
	v_mov_b32_e32 v31, v0
	v_mov_b32_e32 v80, v0
	v_mov_b32_e32 v81, v0
	v_mov_b32_e32 v82, v0
	v_mov_b32_e32 v83, v0
	v_mov_b32_e32 v84, v0
	v_mov_b32_e32 v85, v0
	v_mov_b32_e32 v86, v0
	v_mov_b32_e32 v87, v0
	v_mov_b32_e32 v88, v0
	v_mov_b32_e32 v89, v0
	v_mov_b32_e32 v90, v0
	v_mov_b32_e32 v91, v0
	v_mov_b32_e32 v92, v0
	v_mov_b32_e32 v93, v0
	v_mov_b32_e32 v94, v0
	v_mov_b32_e32 v95, v0
	v_mov_b32_e32 v64, v0
	v_mov_b32_e32 v65, v0
	v_mov_b32_e32 v66, v0
	v_mov_b32_e32 v67, v0
	v_mov_b32_e32 v68, v0
	v_mov_b32_e32 v69, v0
	v_mov_b32_e32 v70, v0
	v_mov_b32_e32 v71, v0
	v_mov_b32_e32 v72, v0
	v_mov_b32_e32 v73, v0
	v_mov_b32_e32 v74, v0
	v_mov_b32_e32 v75, v0
	v_mov_b32_e32 v76, v0
	v_mov_b32_e32 v77, v0
	v_mov_b32_e32 v78, v0
	v_mov_b32_e32 v79, v0
	v_mov_b32_e32 v32, v0
	v_mov_b32_e32 v33, v0
	v_mov_b32_e32 v34, v0
	v_mov_b32_e32 v35, v0
	v_mov_b32_e32 v36, v0
	v_mov_b32_e32 v37, v0
	v_mov_b32_e32 v38, v0
	v_mov_b32_e32 v39, v0
	v_mov_b32_e32 v40, v0
	v_mov_b32_e32 v41, v0
	v_mov_b32_e32 v42, v0
	v_mov_b32_e32 v43, v0
	v_mov_b32_e32 v44, v0
	v_mov_b32_e32 v45, v0
	v_mov_b32_e32 v46, v0
	v_mov_b32_e32 v47, v0
	v_mov_b32_e32 v48, v0
	v_mov_b32_e32 v49, v0
	v_mov_b32_e32 v50, v0
	v_mov_b32_e32 v51, v0
	v_mov_b32_e32 v52, v0
	v_mov_b32_e32 v53, v0
	v_mov_b32_e32 v54, v0
	v_mov_b32_e32 v55, v0
	v_mov_b32_e32 v56, v0
	v_mov_b32_e32 v57, v0
	v_mov_b32_e32 v58, v0
	v_mov_b32_e32 v59, v0
	v_mov_b32_e32 v60, v0
	v_mov_b32_e32 v61, v0
	v_mov_b32_e32 v62, v0
	v_mov_b32_e32 v63, v0
	v_mov_b32_e32 v112, v0
	v_mov_b32_e32 v113, v0
	v_mov_b32_e32 v114, v0
	v_mov_b32_e32 v115, v0
	v_mov_b32_e32 v116, v0
	v_mov_b32_e32 v117, v0
	v_mov_b32_e32 v118, v0
	v_mov_b32_e32 v119, v0
	v_mov_b32_e32 v120, v0
	v_mov_b32_e32 v121, v0
	v_mov_b32_e32 v122, v0
	v_mov_b32_e32 v123, v0
	v_mov_b32_e32 v124, v0
	v_mov_b32_e32 v125, v0
	v_mov_b32_e32 v126, v0
	v_mov_b32_e32 v127, v0
	v_mov_b32_e32 v96, v0
	v_mov_b32_e32 v97, v0
	v_mov_b32_e32 v98, v0
	v_mov_b32_e32 v99, v0
	v_mov_b32_e32 v100, v0
	v_mov_b32_e32 v101, v0
	v_mov_b32_e32 v102, v0
	v_mov_b32_e32 v103, v0
	v_mov_b32_e32 v104, v0
	v_mov_b32_e32 v105, v0
	v_mov_b32_e32 v106, v0
	v_mov_b32_e32 v107, v0
	v_mov_b32_e32 v108, v0
	v_mov_b32_e32 v109, v0
	v_mov_b32_e32 v110, v0
	v_mov_b32_e32 v111, v0

.LBB0_1501:
	v_mov_b32_e32 v95, 0
	s_and_b64 vcc, exec, s[14:15]
	v_mov_b32_e32 v94, 0
	v_mov_b32_e32 v93, 0
	v_mov_b32_e32 v92, 0
	v_mov_b32_e32 v91, 0
	v_mov_b32_e32 v90, 0
	v_mov_b32_e32 v89, 0
	v_mov_b32_e32 v88, 0
	v_mov_b32_e32 v87, 0
	v_mov_b32_e32 v86, 0
	v_mov_b32_e32 v85, 0
	v_mov_b32_e32 v84, 0
	v_mov_b32_e32 v83, 0
	v_mov_b32_e32 v82, 0
	v_mov_b32_e32 v81, 0
	v_mov_b32_e32 v80, 0
	v_mov_b32_e32 v31, 0
	v_mov_b32_e32 v30, 0
	v_mov_b32_e32 v29, 0
	v_mov_b32_e32 v28, 0
	v_mov_b32_e32 v27, 0
	v_mov_b32_e32 v26, 0
	v_mov_b32_e32 v25, 0
	v_mov_b32_e32 v24, 0
	v_mov_b32_e32 v23, 0
	v_mov_b32_e32 v22, 0
	v_mov_b32_e32 v21, 0
	v_mov_b32_e32 v20, 0
	v_mov_b32_e32 v19, 0
	v_mov_b32_e32 v18, 0
	v_mov_b32_e32 v17, 0
	v_mov_b32_e32 v16, 0
	v_mov_b32_e32 v79, 0
	v_mov_b32_e32 v78, 0
	v_mov_b32_e32 v77, 0
	v_mov_b32_e32 v76, 0
	v_mov_b32_e32 v75, 0
	v_mov_b32_e32 v74, 0
	v_mov_b32_e32 v73, 0
	v_mov_b32_e32 v72, 0
	v_mov_b32_e32 v71, 0
	v_mov_b32_e32 v70, 0
	v_mov_b32_e32 v69, 0
	v_mov_b32_e32 v68, 0
	v_mov_b32_e32 v67, 0
	v_mov_b32_e32 v66, 0
	v_mov_b32_e32 v65, 0
	v_mov_b32_e32 v64, 0
	v_mov_b32_e32 v15, 0
	v_mov_b32_e32 v14, 0
	v_mov_b32_e32 v13, 0
	v_mov_b32_e32 v12, 0
	v_mov_b32_e32 v11, 0
	v_mov_b32_e32 v10, 0
	v_mov_b32_e32 v9, 0
	v_mov_b32_e32 v8, 0
	v_mov_b32_e32 v7, 0
	v_mov_b32_e32 v6, 0
	v_mov_b32_e32 v5, 0
	v_mov_b32_e32 v4, 0
	v_mov_b32_e32 v3, 0
	v_mov_b32_e32 v2, 0
	v_mov_b32_e32 v1, 0
	v_mov_b32_e32 v0, 0
	s_cbranch_vccz .LBB0_1509
	s_cmp_gt_i32 s17, 1
	s_cselect_b32 s14, 0x80, 0
	s_add_u32 s12, s12, s14
	s_addc_u32 s13, s13, 0
	v_lshl_add_u64 v[240:241], s[12:13], 0, v[192:193]
	s_add_u32 s10, s10, s14
	v_lshl_add_u64 v[242:243], s[12:13], 0, v[194:195]
	global_load_dwordx4 v[128:131], v[240:241], off
	global_load_dwordx4 v[132:135], v[242:243], off
	v_lshl_add_u64 v[240:241], s[12:13], 0, v[196:197]
	s_addc_u32 s11, s11, 0
	v_lshl_add_u64 v[242:243], s[12:13], 0, v[198:199]
	global_load_dwordx4 v[140:143], v[240:241], off
	global_load_dwordx4 v[136:139], v[242:243], off
	v_lshl_add_u64 v[240:241], s[10:11], 0, v[192:193]
	v_lshl_add_u64 v[242:243], s[10:11], 0, v[194:195]
	global_load_dwordx4 v[148:151], v[240:241], off
	global_load_dwordx4 v[144:147], v[242:243], off
	v_lshl_add_u64 v[240:241], s[10:11], 0, v[196:197]
	v_lshl_add_u64 v[242:243], s[10:11], 0, v[198:199]
	global_load_dwordx4 v[152:155], v[240:241], off
	global_load_dwordx4 v[156:159], v[242:243], off
	s_and_saveexec_b64 s[14:15], s[2:3]
	s_cbranch_execz .LBB0_1504
	v_or_b32_e32 v0, s18, v208
	v_ashrrev_i32_e32 v1, 31, v0
	v_lshlrev_b64 v[0:1], 6, v[0:1]
	v_lshl_add_u64 v[12:13], s[70:71], 0, v[0:1]
	global_load_dwordx4 v[0:3], v[12:13], off
	global_load_dwordx4 v[4:7], v[12:13], off offset:16
	global_load_dwordx4 v[8:11], v[12:13], off offset:32
	s_nop 0
	global_load_dwordx4 v[12:15], v[12:13], off offset:48
	s_waitcnt vmcnt(3)
	v_mov_b32_e32 v16, v1
	v_mov_b32_e32 v17, v2
	s_waitcnt vmcnt(2)
	v_mov_b32_e32 v18, v5
	v_mov_b32_e32 v19, v6
	v_mov_b32_e32 v1, v3
	v_mov_b32_e32 v5, v7
	s_waitcnt vmcnt(1)
	v_mov_b32_e32 v2, v9
	v_mov_b32_e32 v6, v11
	v_pk_add_f32 v[0:1], v[16:17], v[0:1]
	v_pk_add_f32 v[4:5], v[18:19], v[4:5]
	v_pk_add_f32 v[2:3], v[8:9], v[2:3]
	v_pk_add_f32 v[6:7], v[10:11], v[6:7]
	v_pk_add_f32 v[0:1], v[0:1], v[0:1] op_sel:[0,1] op_sel_hi:[1,0]
	v_pk_add_f32 v[4:5], v[4:5], v[4:5] op_sel:[0,1] op_sel_hi:[1,0]
	s_waitcnt vmcnt(0)
	v_mov_b32_e32 v3, v14
	v_mov_b32_e32 v7, v15
	v_mov_b32_e32 v1, v12
	v_mov_b32_e32 v5, v13
	v_pk_add_f32 v[2:3], v[2:3], v[6:7]
	v_pk_add_f32 v[0:1], v[0:1], v[4:5]
	s_nop 0
	v_pk_add_f32 v[0:1], v[0:1], v[2:3]
	s_nop 0
	v_add_f32_e32 v0, v0, v1
	v_fmamk_f32 v0, v0, 0x3a800000, v202
	v_mul_f32_e32 v1, 0x4b800000, v0
	v_cmp_gt_f32_e32 vcc, s30, v0
	s_nop 1
	v_cndmask_b32_e32 v0, v0, v1, vcc
	v_rsq_f32_e32 v0, v0
	s_nop 0
	v_mul_f32_e32 v1, 0x45800000, v0
	v_cndmask_b32_e32 v0, v0, v1, vcc
	ds_write_b32 v201, v0
.LBB0_1504:
	s_or_b64 exec, exec, s[14:15]
	v_mul_lo_u32 v0, v204, s31
	v_lshl_add_u32 v204, v211, 1, v0
	v_or_b32_e32 v0, v210, v206
	v_lshlrev_b32_e32 v1, 3, v207
	v_lshl_or_b32 v2, v205, 6, v206
	s_waitcnt vmcnt(8)
	ds_write_b128 v204, v[160:163]
	ds_write_b128 v204, v[180:183] offset:9216
	ds_write_b128 v204, v[184:187] offset:18432
	ds_write_b128 v204, v[188:191] offset:27648
	ds_write_b128 v204, v[164:167] offset:36864
	ds_write_b128 v204, v[168:171] offset:46080
	ds_write_b128 v204, v[172:175] offset:55296
	ds_write_b128 v204, v[176:179] offset:64512
	s_mov_b32 s10, 0
	s_mov_b32 s11, 0
	s_cmp_lt_i32 s17, 3
	v_mul_lo_u32 v176, v0, s31
	v_mul_u32_u24_e32 v177, 0x90, v2
	v_lshlrev_b32_e32 v178, 1, v1
	s_waitcnt lgkmcnt(0)
	s_barrier
	s_cbranch_scc1 .LBB0_2804
	s_add_i32 s10, s17, -2
	s_add_u32 s6, s6, 0x7dbbb00
	s_addc_u32 s7, s7, 0
	v_lshl_add_u64 v[160:161], s[6:7], 0, v[192:193]
	v_lshl_add_u64 v[162:163], s[6:7], 0, v[194:195]
	v_lshl_add_u64 v[164:165], s[6:7], 0, v[196:197]
	v_lshl_add_u64 v[166:167], s[6:7], 0, v[198:199]
	s_add_u32 s6, s8, 0x8a0100
	s_addc_u32 s7, s9, 0
	v_mov_b32_e32 v0, 0
	v_lshl_add_u64 v[168:169], s[6:7], 0, v[192:193]
	v_lshl_add_u64 v[170:171], s[6:7], 0, v[194:195]
	v_lshl_add_u64 v[172:173], s[6:7], 0, v[196:197]
	v_lshl_add_u64 v[174:175], s[6:7], 0, v[198:199]
	s_mov_b64 s[6:7], s[90:91]
	v_mov_b32_e32 v1, v0
	v_mov_b32_e32 v2, v0
	v_mov_b32_e32 v3, v0
	v_mov_b32_e32 v4, v0
	v_mov_b32_e32 v5, v0
	v_mov_b32_e32 v6, v0
	v_mov_b32_e32 v7, v0
	v_mov_b32_e32 v8, v0
	v_mov_b32_e32 v9, v0
	v_mov_b32_e32 v10, v0
	v_mov_b32_e32 v11, v0
	v_mov_b32_e32 v12, v0
	v_mov_b32_e32 v13, v0
	v_mov_b32_e32 v14, v0
	v_mov_b32_e32 v15, v0
	v_mov_b32_e32 v64, v0
	v_mov_b32_e32 v65, v0
	v_mov_b32_e32 v66, v0
	v_mov_b32_e32 v67, v0
	v_mov_b32_e32 v68, v0
	v_mov_b32_e32 v69, v0
	v_mov_b32_e32 v70, v0
	v_mov_b32_e32 v71, v0
	v_mov_b32_e32 v72, v0
	v_mov_b32_e32 v73, v0
	v_mov_b32_e32 v74, v0
	v_mov_b32_e32 v75, v0
	v_mov_b32_e32 v76, v0
	v_mov_b32_e32 v77, v0
	v_mov_b32_e32 v78, v0
	v_mov_b32_e32 v79, v0
	v_mov_b32_e32 v16, v0
	v_mov_b32_e32 v17, v0
	v_mov_b32_e32 v18, v0
	v_mov_b32_e32 v19, v0
	v_mov_b32_e32 v20, v0
	v_mov_b32_e32 v21, v0
	v_mov_b32_e32 v22, v0
	v_mov_b32_e32 v23, v0
	v_mov_b32_e32 v24, v0
	v_mov_b32_e32 v25, v0
	v_mov_b32_e32 v26, v0
	v_mov_b32_e32 v27, v0
	v_mov_b32_e32 v28, v0
	v_mov_b32_e32 v29, v0
	v_mov_b32_e32 v30, v0
	v_mov_b32_e32 v31, v0
	v_mov_b32_e32 v80, v0
	v_mov_b32_e32 v81, v0
	v_mov_b32_e32 v82, v0
	v_mov_b32_e32 v83, v0
	v_mov_b32_e32 v84, v0
	v_mov_b32_e32 v85, v0
	v_mov_b32_e32 v86, v0
	v_mov_b32_e32 v87, v0
	v_mov_b32_e32 v88, v0
	v_mov_b32_e32 v89, v0
	v_mov_b32_e32 v90, v0
	v_mov_b32_e32 v91, v0
	v_mov_b32_e32 v92, v0
	v_mov_b32_e32 v93, v0
	v_mov_b32_e32 v94, v0
	v_mov_b32_e32 v95, v0
	v_mov_b32_e32 v32, v0
	v_mov_b32_e32 v33, v0
	v_mov_b32_e32 v34, v0
	v_mov_b32_e32 v35, v0
	v_mov_b32_e32 v36, v0
	v_mov_b32_e32 v37, v0
	v_mov_b32_e32 v38, v0
	v_mov_b32_e32 v39, v0
	v_mov_b32_e32 v40, v0
	v_mov_b32_e32 v41, v0
	v_mov_b32_e32 v42, v0
	v_mov_b32_e32 v43, v0
	v_mov_b32_e32 v44, v0
	v_mov_b32_e32 v45, v0
	v_mov_b32_e32 v46, v0
	v_mov_b32_e32 v47, v0
	v_mov_b32_e32 v96, v0
	v_mov_b32_e32 v97, v0
	v_mov_b32_e32 v98, v0
	v_mov_b32_e32 v99, v0
	v_mov_b32_e32 v100, v0
	v_mov_b32_e32 v101, v0
	v_mov_b32_e32 v102, v0
	v_mov_b32_e32 v103, v0
	v_mov_b32_e32 v104, v0
	v_mov_b32_e32 v105, v0
	v_mov_b32_e32 v106, v0
	v_mov_b32_e32 v107, v0
	v_mov_b32_e32 v108, v0
	v_mov_b32_e32 v109, v0
	v_mov_b32_e32 v110, v0
	v_mov_b32_e32 v111, v0
	v_mov_b32_e32 v48, v0
	v_mov_b32_e32 v49, v0
	v_mov_b32_e32 v50, v0
	v_mov_b32_e32 v51, v0
	v_mov_b32_e32 v52, v0
	v_mov_b32_e32 v53, v0
	v_mov_b32_e32 v54, v0
	v_mov_b32_e32 v55, v0
	v_mov_b32_e32 v56, v0
	v_mov_b32_e32 v57, v0
	v_mov_b32_e32 v58, v0
	v_mov_b32_e32 v59, v0
	v_mov_b32_e32 v60, v0
	v_mov_b32_e32 v61, v0
	v_mov_b32_e32 v62, v0
	v_mov_b32_e32 v63, v0
	v_mov_b32_e32 v112, v0
	v_mov_b32_e32 v113, v0
	v_mov_b32_e32 v114, v0
	v_mov_b32_e32 v115, v0
	v_mov_b32_e32 v116, v0
	v_mov_b32_e32 v117, v0
	v_mov_b32_e32 v118, v0
	v_mov_b32_e32 v119, v0
	v_mov_b32_e32 v120, v0
	v_mov_b32_e32 v121, v0
	v_mov_b32_e32 v122, v0
	v_mov_b32_e32 v123, v0
	v_mov_b32_e32 v124, v0
	v_mov_b32_e32 v125, v0
	v_mov_b32_e32 v126, v0
	v_mov_b32_e32 v127, v0

.LBB0_3037:
	v_mov_b32_e32 v95, 0
	s_and_b64 vcc, exec, s[18:19]
	v_mov_b32_e32 v94, 0
	v_mov_b32_e32 v93, 0
	v_mov_b32_e32 v92, 0
	v_mov_b32_e32 v91, 0
	v_mov_b32_e32 v90, 0
	v_mov_b32_e32 v89, 0
	v_mov_b32_e32 v88, 0
	v_mov_b32_e32 v87, 0
	v_mov_b32_e32 v86, 0
	v_mov_b32_e32 v85, 0
	v_mov_b32_e32 v84, 0
	v_mov_b32_e32 v83, 0
	v_mov_b32_e32 v82, 0
	v_mov_b32_e32 v81, 0
	v_mov_b32_e32 v80, 0
	v_mov_b32_e32 v31, 0
	v_mov_b32_e32 v30, 0
	v_mov_b32_e32 v29, 0
	v_mov_b32_e32 v28, 0
	v_mov_b32_e32 v27, 0
	v_mov_b32_e32 v26, 0
	v_mov_b32_e32 v25, 0
	v_mov_b32_e32 v24, 0
	v_mov_b32_e32 v23, 0
	v_mov_b32_e32 v22, 0
	v_mov_b32_e32 v21, 0
	v_mov_b32_e32 v20, 0
	v_mov_b32_e32 v19, 0
	v_mov_b32_e32 v18, 0
	v_mov_b32_e32 v17, 0
	v_mov_b32_e32 v16, 0
	v_mov_b32_e32 v79, 0
	v_mov_b32_e32 v78, 0
	v_mov_b32_e32 v77, 0
	v_mov_b32_e32 v76, 0
	v_mov_b32_e32 v75, 0
	v_mov_b32_e32 v74, 0
	v_mov_b32_e32 v73, 0
	v_mov_b32_e32 v72, 0
	v_mov_b32_e32 v71, 0
	v_mov_b32_e32 v70, 0
	v_mov_b32_e32 v69, 0
	v_mov_b32_e32 v68, 0
	v_mov_b32_e32 v67, 0
	v_mov_b32_e32 v66, 0
	v_mov_b32_e32 v65, 0
	v_mov_b32_e32 v64, 0
	v_mov_b32_e32 v15, 0
	v_mov_b32_e32 v14, 0
	v_mov_b32_e32 v13, 0
	v_mov_b32_e32 v12, 0
	v_mov_b32_e32 v11, 0
	v_mov_b32_e32 v10, 0
	v_mov_b32_e32 v9, 0
	v_mov_b32_e32 v8, 0
	v_mov_b32_e32 v7, 0
	v_mov_b32_e32 v6, 0
	v_mov_b32_e32 v5, 0
	v_mov_b32_e32 v4, 0
	v_mov_b32_e32 v3, 0
	v_mov_b32_e32 v2, 0
	v_mov_b32_e32 v1, 0
	v_mov_b32_e32 v0, 0
	s_cbranch_vccz .LBB0_3045
	s_cmp_gt_i32 s34, 1
	s_cselect_b32 s1, 0x80, 0
	s_add_u32 s16, s16, s1
	s_addc_u32 s17, s17, 0
	v_lshl_add_u64 v[240:241], s[16:17], 0, v[192:193]
	s_add_u32 s14, s14, s1
	v_lshl_add_u64 v[242:243], s[16:17], 0, v[196:197]
	global_load_dwordx4 v[128:131], v[240:241], off
	global_load_dwordx4 v[132:135], v[242:243], off
	v_lshl_add_u64 v[240:241], s[16:17], 0, v[198:199]
	s_addc_u32 s15, s15, 0
	v_lshl_add_u64 v[242:243], s[16:17], 0, v[200:201]
	global_load_dwordx4 v[140:143], v[240:241], off
	global_load_dwordx4 v[136:139], v[242:243], off
	v_lshl_add_u64 v[240:241], s[14:15], 0, v[194:195]
	v_lshl_add_u64 v[242:243], s[14:15], 0, v[202:203]
	global_load_dwordx4 v[148:151], v[240:241], off
	global_load_dwordx4 v[144:147], v[242:243], off
	v_lshl_add_u64 v[240:241], s[14:15], 0, v[204:205]
	v_lshl_add_u64 v[242:243], s[14:15], 0, v[206:207]
	global_load_dwordx4 v[152:155], v[240:241], off
	global_load_dwordx4 v[156:159], v[242:243], off
	s_and_saveexec_b64 s[18:19], s[2:3]
	s_cbranch_execz .LBB0_3040
	v_or_b32_e32 v0, s8, v208
	v_ashrrev_i32_e32 v1, 31, v0
	v_lshl_add_u64 v[0:1], v[0:1], 4, s[6:7]
	global_load_dwordx4 v[0:3], v[0:1], off
	s_waitcnt vmcnt(0)
	v_mov_b32_e32 v4, v1
	v_mov_b32_e32 v5, v2
	v_mov_b32_e32 v1, v3
	v_pk_add_f32 v[0:1], v[4:5], v[0:1]
	s_nop 0
	v_add_f32_e32 v0, v0, v1
	v_fmamk_f32 v0, v0, 0x3b800000, v216
	v_mul_f32_e32 v1, 0x4b800000, v0
	v_cmp_gt_f32_e32 vcc, s23, v0
	s_nop 1
	v_cndmask_b32_e32 v0, v0, v1, vcc
	v_rsq_f32_e32 v0, v0
	s_nop 0
	v_mul_f32_e32 v1, 0x45800000, v0
	v_cndmask_b32_e32 v0, v0, v1, vcc
	ds_write_b32 v215, v0
.LBB0_3040:
	s_or_b64 exec, exec, s[18:19]
	v_mul_lo_u32 v0, v223, s24
	v_lshl_add_u32 v223, v228, 1, v0
	v_or_b32_e32 v0, v227, v225
	v_lshlrev_b32_e32 v1, 3, v226
	v_lshl_or_b32 v2, v224, 6, v225
	s_waitcnt vmcnt(8)
	ds_write_b128 v223, v[188:191]
	ds_write_b128 v223, v[160:163] offset:9216
	ds_write_b128 v223, v[164:167] offset:18432
	ds_write_b128 v223, v[168:171] offset:27648
	ds_write_b128 v223, v[172:175] offset:36864
	ds_write_b128 v223, v[176:179] offset:46080
	ds_write_b128 v223, v[180:183] offset:55296
	ds_write_b128 v223, v[184:187] offset:64512
	s_mov_b32 s1, 0
	s_mov_b32 s9, 0
	s_cmp_lt_i32 s34, 3
	v_mul_lo_u32 v176, v0, s24
	v_mul_u32_u24_e32 v177, 0x90, v2
	v_lshlrev_b32_e32 v178, 1, v1
	s_waitcnt lgkmcnt(0)
	s_barrier
	s_cbranch_scc1 .LBB0_3053
	s_add_i32 s1, s34, -2
	s_add_u32 s10, s10, 0x13dbb00
	s_addc_u32 s11, s11, 0
	v_lshl_add_u64 v[160:161], s[10:11], 0, v[192:193]
	v_lshl_add_u64 v[162:163], s[10:11], 0, v[196:197]
	v_lshl_add_u64 v[164:165], s[10:11], 0, v[198:199]
	v_lshl_add_u64 v[166:167], s[10:11], 0, v[200:201]
	s_add_u32 s10, s12, 0x400100
	s_addc_u32 s11, s13, 0
	v_mov_b32_e32 v0, 0
	v_lshl_add_u64 v[168:169], s[10:11], 0, v[194:195]
	v_lshl_add_u64 v[170:171], s[10:11], 0, v[202:203]
	v_lshl_add_u64 v[172:173], s[10:11], 0, v[204:205]
	v_lshl_add_u64 v[174:175], s[10:11], 0, v[206:207]
	s_mov_b64 s[10:11], s[90:91]
	v_mov_b32_e32 v1, v0
	v_mov_b32_e32 v2, v0
	v_mov_b32_e32 v3, v0
	v_mov_b32_e32 v4, v0
	v_mov_b32_e32 v5, v0
	v_mov_b32_e32 v6, v0
	v_mov_b32_e32 v7, v0
	v_mov_b32_e32 v8, v0
	v_mov_b32_e32 v9, v0
	v_mov_b32_e32 v10, v0
	v_mov_b32_e32 v11, v0
	v_mov_b32_e32 v12, v0
	v_mov_b32_e32 v13, v0
	v_mov_b32_e32 v14, v0
	v_mov_b32_e32 v15, v0
	v_mov_b32_e32 v64, v0
	v_mov_b32_e32 v65, v0
	v_mov_b32_e32 v66, v0
	v_mov_b32_e32 v67, v0
	v_mov_b32_e32 v68, v0
	v_mov_b32_e32 v69, v0
	v_mov_b32_e32 v70, v0
	v_mov_b32_e32 v71, v0
	v_mov_b32_e32 v72, v0
	v_mov_b32_e32 v73, v0
	v_mov_b32_e32 v74, v0
	v_mov_b32_e32 v75, v0
	v_mov_b32_e32 v76, v0
	v_mov_b32_e32 v77, v0
	v_mov_b32_e32 v78, v0
	v_mov_b32_e32 v79, v0
	v_mov_b32_e32 v16, v0
	v_mov_b32_e32 v17, v0
	v_mov_b32_e32 v18, v0
	v_mov_b32_e32 v19, v0
	v_mov_b32_e32 v20, v0
	v_mov_b32_e32 v21, v0
	v_mov_b32_e32 v22, v0
	v_mov_b32_e32 v23, v0
	v_mov_b32_e32 v24, v0
	v_mov_b32_e32 v25, v0
	v_mov_b32_e32 v26, v0
	v_mov_b32_e32 v27, v0
	v_mov_b32_e32 v28, v0
	v_mov_b32_e32 v29, v0
	v_mov_b32_e32 v30, v0
	v_mov_b32_e32 v31, v0
	v_mov_b32_e32 v80, v0
	v_mov_b32_e32 v81, v0
	v_mov_b32_e32 v82, v0
	v_mov_b32_e32 v83, v0
	v_mov_b32_e32 v84, v0
	v_mov_b32_e32 v85, v0
	v_mov_b32_e32 v86, v0
	v_mov_b32_e32 v87, v0
	v_mov_b32_e32 v88, v0
	v_mov_b32_e32 v89, v0
	v_mov_b32_e32 v90, v0
	v_mov_b32_e32 v91, v0
	v_mov_b32_e32 v92, v0
	v_mov_b32_e32 v93, v0
	v_mov_b32_e32 v94, v0
	v_mov_b32_e32 v95, v0
	v_mov_b32_e32 v32, v0
	v_mov_b32_e32 v33, v0
	v_mov_b32_e32 v34, v0
	v_mov_b32_e32 v35, v0
	v_mov_b32_e32 v36, v0
	v_mov_b32_e32 v37, v0
	v_mov_b32_e32 v38, v0
	v_mov_b32_e32 v39, v0
	v_mov_b32_e32 v40, v0
	v_mov_b32_e32 v41, v0
	v_mov_b32_e32 v42, v0
	v_mov_b32_e32 v43, v0
	v_mov_b32_e32 v44, v0
	v_mov_b32_e32 v45, v0
	v_mov_b32_e32 v46, v0
	v_mov_b32_e32 v47, v0
	v_mov_b32_e32 v96, v0
	v_mov_b32_e32 v97, v0
	v_mov_b32_e32 v98, v0
	v_mov_b32_e32 v99, v0
	v_mov_b32_e32 v100, v0
	v_mov_b32_e32 v101, v0
	v_mov_b32_e32 v102, v0
	v_mov_b32_e32 v103, v0
	v_mov_b32_e32 v104, v0
	v_mov_b32_e32 v105, v0
	v_mov_b32_e32 v106, v0
	v_mov_b32_e32 v107, v0
	v_mov_b32_e32 v108, v0
	v_mov_b32_e32 v109, v0
	v_mov_b32_e32 v110, v0
	v_mov_b32_e32 v111, v0
	v_mov_b32_e32 v48, v0
	v_mov_b32_e32 v49, v0
	v_mov_b32_e32 v50, v0
	v_mov_b32_e32 v51, v0
	v_mov_b32_e32 v52, v0
	v_mov_b32_e32 v53, v0
	v_mov_b32_e32 v54, v0
	v_mov_b32_e32 v55, v0
	v_mov_b32_e32 v56, v0
	v_mov_b32_e32 v57, v0
	v_mov_b32_e32 v58, v0
	v_mov_b32_e32 v59, v0
	v_mov_b32_e32 v60, v0
	v_mov_b32_e32 v61, v0
	v_mov_b32_e32 v62, v0
	v_mov_b32_e32 v63, v0
	v_mov_b32_e32 v112, v0
	v_mov_b32_e32 v113, v0
	v_mov_b32_e32 v114, v0
	v_mov_b32_e32 v115, v0
	v_mov_b32_e32 v116, v0
	v_mov_b32_e32 v117, v0
	v_mov_b32_e32 v118, v0
	v_mov_b32_e32 v119, v0
	v_mov_b32_e32 v120, v0
	v_mov_b32_e32 v121, v0
	v_mov_b32_e32 v122, v0
	v_mov_b32_e32 v123, v0
	v_mov_b32_e32 v124, v0
	v_mov_b32_e32 v125, v0
	v_mov_b32_e32 v126, v0
	v_mov_b32_e32 v127, v0

.LBB0_3068:
	v_mov_b32_e32 v111, 0
	s_and_b64 vcc, exec, s[10:11]
	v_mov_b32_e32 v110, 0
	v_mov_b32_e32 v109, 0
	v_mov_b32_e32 v108, 0
	v_mov_b32_e32 v107, 0
	v_mov_b32_e32 v106, 0
	v_mov_b32_e32 v105, 0
	v_mov_b32_e32 v104, 0
	v_mov_b32_e32 v103, 0
	v_mov_b32_e32 v102, 0
	v_mov_b32_e32 v101, 0
	v_mov_b32_e32 v100, 0
	v_mov_b32_e32 v99, 0
	v_mov_b32_e32 v98, 0
	v_mov_b32_e32 v97, 0
	v_mov_b32_e32 v96, v111
	v_mov_b32_e32 v47, 0
	v_mov_b32_e32 v46, 0
	v_mov_b32_e32 v45, 0
	v_mov_b32_e32 v44, 0
	v_mov_b32_e32 v43, 0
	v_mov_b32_e32 v42, 0
	v_mov_b32_e32 v41, 0
	v_mov_b32_e32 v40, 0
	v_mov_b32_e32 v39, 0
	v_mov_b32_e32 v38, 0
	v_mov_b32_e32 v37, 0
	v_mov_b32_e32 v36, 0
	v_mov_b32_e32 v35, 0
	v_mov_b32_e32 v34, 0
	v_mov_b32_e32 v33, 0
	v_mov_b32_e32 v32, v111
	v_mov_b32_e32 v79, 0
	v_mov_b32_e32 v78, 0
	v_mov_b32_e32 v77, 0
	v_mov_b32_e32 v76, 0
	v_mov_b32_e32 v75, 0
	v_mov_b32_e32 v74, 0
	v_mov_b32_e32 v73, 0
	v_mov_b32_e32 v72, 0
	v_mov_b32_e32 v71, 0
	v_mov_b32_e32 v70, 0
	v_mov_b32_e32 v69, 0
	v_mov_b32_e32 v68, 0
	v_mov_b32_e32 v67, 0
	v_mov_b32_e32 v66, 0
	v_mov_b32_e32 v65, 0
	v_mov_b32_e32 v64, v111
	v_mov_b32_e32 v31, 0
	v_mov_b32_e32 v30, 0
	v_mov_b32_e32 v29, 0
	v_mov_b32_e32 v28, 0
	v_mov_b32_e32 v27, 0
	v_mov_b32_e32 v26, 0
	v_mov_b32_e32 v25, 0
	v_mov_b32_e32 v24, 0
	v_mov_b32_e32 v23, 0
	v_mov_b32_e32 v22, 0
	v_mov_b32_e32 v21, 0
	v_mov_b32_e32 v20, 0
	v_mov_b32_e32 v19, 0
	v_mov_b32_e32 v18, 0
	v_mov_b32_e32 v17, 0
	v_mov_b32_e32 v16, v111
	s_cbranch_vccz .LBB0_3076
	s_cmp_gt_i32 s13, 1
	s_cselect_b32 s10, 0x80, 0
	s_add_u32 s8, s8, s10
	s_addc_u32 s9, s9, 0
	v_lshl_add_u64 v[240:241], s[8:9], 0, v[192:193]
	s_add_u32 s6, s6, s10
	v_lshl_add_u64 v[242:243], s[8:9], 0, v[196:197]
	global_load_dwordx4 v[128:131], v[240:241], off
	global_load_dwordx4 v[132:135], v[242:243], off
	v_lshl_add_u64 v[240:241], s[8:9], 0, v[198:199]
	s_addc_u32 s7, s7, 0
	v_lshl_add_u64 v[242:243], s[8:9], 0, v[200:201]
	global_load_dwordx4 v[140:143], v[240:241], off
	global_load_dwordx4 v[136:139], v[242:243], off
	v_lshl_add_u64 v[240:241], s[6:7], 0, v[194:195]
	v_lshl_add_u64 v[242:243], s[6:7], 0, v[202:203]
	global_load_dwordx4 v[148:151], v[240:241], off
	global_load_dwordx4 v[144:147], v[242:243], off
	v_lshl_add_u64 v[240:241], s[6:7], 0, v[204:205]
	v_lshl_add_u64 v[242:243], s[6:7], 0, v[206:207]
	global_load_dwordx4 v[152:155], v[240:241], off
	global_load_dwordx4 v[156:159], v[242:243], off
	s_and_saveexec_b64 s[10:11], s[2:3]
	s_cbranch_execz .LBB0_3071
	v_or_b32_e32 v0, s78, v208
	v_ashrrev_i32_e32 v1, 31, v0
	v_lshl_add_u64 v[0:1], v[0:1], 3, s[74:75]
	global_load_dwordx2 v[0:1], v[0:1], off
	s_waitcnt vmcnt(0)
	v_add_f32_e32 v0, v1, v0
	v_fmamk_f32 v0, v0, 0x3c000000, v216
	v_mul_f32_e32 v1, 0x4b800000, v0
	v_cmp_gt_f32_e32 vcc, s73, v0
	s_nop 1
	v_cndmask_b32_e32 v0, v0, v1, vcc
	v_rsq_f32_e32 v0, v0
	s_nop 0
	v_mul_f32_e32 v1, 0x45800000, v0
	v_cndmask_b32_e32 v0, v0, v1, vcc
	ds_write_b32 v215, v0
.LBB0_3071:
	s_or_b64 exec, exec, s[10:11]
	v_mul_lo_u32 v0, v217, s84
	v_lshl_add_u32 v217, v222, 1, v0
	v_or_b32_e32 v0, v221, v219
	v_lshlrev_b32_e32 v1, 3, v220
	v_lshl_or_b32 v2, v218, 6, v219
	s_waitcnt vmcnt(8)
	ds_write_b128 v217, v[188:191]
	ds_write_b128 v217, v[160:163] offset:9216
	ds_write_b128 v217, v[164:167] offset:18432
	ds_write_b128 v217, v[168:171] offset:27648
	ds_write_b128 v217, v[172:175] offset:36864
	ds_write_b128 v217, v[176:179] offset:46080
	ds_write_b128 v217, v[180:183] offset:55296
	ds_write_b128 v217, v[184:187] offset:64512
	s_mov_b32 s6, 0
	s_mov_b32 s7, 0
	s_cmp_lt_i32 s13, 3
	v_mul_lo_u32 v176, v0, s84
	v_mul_u32_u24_e32 v177, 0x90, v2
	v_lshlrev_b32_e32 v178, 1, v1
	s_waitcnt lgkmcnt(0)
	s_barrier
	s_cbranch_scc1 .LBB0_3144
	s_add_i32 s6, s13, -2
	s_add_u32 s0, s0, 0x13dbd00
	s_addc_u32 s1, s1, 0
	v_lshl_add_u64 v[160:161], s[0:1], 0, v[192:193]
	v_lshl_add_u64 v[162:163], s[0:1], 0, v[196:197]
	v_lshl_add_u64 v[164:165], s[0:1], 0, v[198:199]
	v_lshl_add_u64 v[166:167], s[0:1], 0, v[200:201]
	s_add_u32 s0, s4, 0x460100
	s_addc_u32 s1, s5, 0
	v_mov_b32_e32 v16, 0
	v_lshl_add_u64 v[168:169], s[0:1], 0, v[194:195]
	v_lshl_add_u64 v[170:171], s[0:1], 0, v[202:203]
	v_lshl_add_u64 v[172:173], s[0:1], 0, v[204:205]
	v_lshl_add_u64 v[174:175], s[0:1], 0, v[206:207]
	s_mov_b64 s[0:1], s[90:91]
	v_mov_b32_e32 v17, v16
	v_mov_b32_e32 v18, v16
	v_mov_b32_e32 v19, v16
	v_mov_b32_e32 v20, v16
	v_mov_b32_e32 v21, v16
	v_mov_b32_e32 v22, v16
	v_mov_b32_e32 v23, v16
	v_mov_b32_e32 v24, v16
	v_mov_b32_e32 v25, v16
	v_mov_b32_e32 v26, v16
	v_mov_b32_e32 v27, v16
	v_mov_b32_e32 v28, v16
	v_mov_b32_e32 v29, v16
	v_mov_b32_e32 v30, v16
	v_mov_b32_e32 v31, v16
	v_mov_b32_e32 v64, v16
	v_mov_b32_e32 v65, v16
	v_mov_b32_e32 v66, v16
	v_mov_b32_e32 v67, v16
	v_mov_b32_e32 v68, v16
	v_mov_b32_e32 v69, v16
	v_mov_b32_e32 v70, v16
	v_mov_b32_e32 v71, v16
	v_mov_b32_e32 v72, v16
	v_mov_b32_e32 v73, v16
	v_mov_b32_e32 v74, v16
	v_mov_b32_e32 v75, v16
	v_mov_b32_e32 v76, v16
	v_mov_b32_e32 v77, v16
	v_mov_b32_e32 v78, v16
	v_mov_b32_e32 v79, v16
	v_mov_b32_e32 v32, v16
	v_mov_b32_e32 v33, v16
	v_mov_b32_e32 v34, v16
	v_mov_b32_e32 v35, v16
	v_mov_b32_e32 v36, v16
	v_mov_b32_e32 v37, v16
	v_mov_b32_e32 v38, v16
	v_mov_b32_e32 v39, v16
	v_mov_b32_e32 v40, v16
	v_mov_b32_e32 v41, v16
	v_mov_b32_e32 v42, v16
	v_mov_b32_e32 v43, v16
	v_mov_b32_e32 v44, v16
	v_mov_b32_e32 v45, v16
	v_mov_b32_e32 v46, v16
	v_mov_b32_e32 v47, v16
	v_mov_b32_e32 v96, v16
	v_mov_b32_e32 v97, v16
	v_mov_b32_e32 v98, v16
	v_mov_b32_e32 v99, v16
	v_mov_b32_e32 v100, v16
	v_mov_b32_e32 v101, v16
	v_mov_b32_e32 v102, v16
	v_mov_b32_e32 v103, v16
	v_mov_b32_e32 v104, v16
	v_mov_b32_e32 v105, v16
	v_mov_b32_e32 v106, v16
	v_mov_b32_e32 v107, v16
	v_mov_b32_e32 v108, v16
	v_mov_b32_e32 v109, v16
	v_mov_b32_e32 v110, v16
	v_mov_b32_e32 v111, v16
	v_mov_b32_e32 v0, v16
	v_mov_b32_e32 v1, v16
	v_mov_b32_e32 v2, v16
	v_mov_b32_e32 v3, v16
	v_mov_b32_e32 v4, v16
	v_mov_b32_e32 v5, v16
	v_mov_b32_e32 v6, v16
	v_mov_b32_e32 v7, v16
	v_mov_b32_e32 v8, v16
	v_mov_b32_e32 v9, v16
	v_mov_b32_e32 v10, v16
	v_mov_b32_e32 v11, v16
	v_mov_b32_e32 v12, v16
	v_mov_b32_e32 v13, v16
	v_mov_b32_e32 v14, v16
	v_mov_b32_e32 v15, v16
	v_mov_b32_e32 v80, v16
	v_mov_b32_e32 v81, v16
	v_mov_b32_e32 v82, v16
	v_mov_b32_e32 v83, v16
	v_mov_b32_e32 v84, v16
	v_mov_b32_e32 v85, v16
	v_mov_b32_e32 v86, v16
	v_mov_b32_e32 v87, v16
	v_mov_b32_e32 v88, v16
	v_mov_b32_e32 v89, v16
	v_mov_b32_e32 v90, v16
	v_mov_b32_e32 v91, v16
	v_mov_b32_e32 v92, v16
	v_mov_b32_e32 v93, v16
	v_mov_b32_e32 v94, v16
	v_mov_b32_e32 v95, v16
	v_mov_b32_e32 v48, v16
	v_mov_b32_e32 v49, v16
	v_mov_b32_e32 v50, v16
	v_mov_b32_e32 v51, v16
	v_mov_b32_e32 v52, v16
	v_mov_b32_e32 v53, v16
	v_mov_b32_e32 v54, v16
	v_mov_b32_e32 v55, v16
	v_mov_b32_e32 v56, v16
	v_mov_b32_e32 v57, v16
	v_mov_b32_e32 v58, v16
	v_mov_b32_e32 v59, v16
	v_mov_b32_e32 v60, v16
	v_mov_b32_e32 v61, v16
	v_mov_b32_e32 v62, v16
	v_mov_b32_e32 v63, v16
	v_mov_b32_e32 v112, v16
	v_mov_b32_e32 v113, v16
	v_mov_b32_e32 v114, v16
	v_mov_b32_e32 v115, v16
	v_mov_b32_e32 v116, v16
	v_mov_b32_e32 v117, v16
	v_mov_b32_e32 v118, v16
	v_mov_b32_e32 v119, v16
	v_mov_b32_e32 v120, v16
	v_mov_b32_e32 v121, v16
	v_mov_b32_e32 v122, v16
	v_mov_b32_e32 v123, v16
	v_mov_b32_e32 v124, v16
	v_mov_b32_e32 v125, v16
	v_mov_b32_e32 v126, v16
	v_mov_b32_e32 v127, v16

.LBB0_4483:
	v_mov_b32_e32 v79, 0
	s_and_b64 vcc, exec, s[18:19]
	v_mov_b32_e32 v78, 0
	v_mov_b32_e32 v77, 0
	v_mov_b32_e32 v76, 0
	v_mov_b32_e32 v75, 0
	v_mov_b32_e32 v74, 0
	v_mov_b32_e32 v73, 0
	v_mov_b32_e32 v72, 0
	v_mov_b32_e32 v71, 0
	v_mov_b32_e32 v70, 0
	v_mov_b32_e32 v69, 0
	v_mov_b32_e32 v68, 0
	v_mov_b32_e32 v67, 0
	v_mov_b32_e32 v66, 0
	v_mov_b32_e32 v65, 0
	v_mov_b32_e32 v64, 0
	v_mov_b32_e32 v95, 0
	v_mov_b32_e32 v94, 0
	v_mov_b32_e32 v93, 0
	v_mov_b32_e32 v92, 0
	v_mov_b32_e32 v91, 0
	v_mov_b32_e32 v90, 0
	v_mov_b32_e32 v89, 0
	v_mov_b32_e32 v88, 0
	v_mov_b32_e32 v87, 0
	v_mov_b32_e32 v86, 0
	v_mov_b32_e32 v85, 0
	v_mov_b32_e32 v84, 0
	v_mov_b32_e32 v83, 0
	v_mov_b32_e32 v82, 0
	v_mov_b32_e32 v81, 0
	v_mov_b32_e32 v80, 0
	v_mov_b32_e32 v31, 0
	v_mov_b32_e32 v30, 0
	v_mov_b32_e32 v29, 0
	v_mov_b32_e32 v28, 0
	v_mov_b32_e32 v27, 0
	v_mov_b32_e32 v26, 0
	v_mov_b32_e32 v25, 0
	v_mov_b32_e32 v24, 0
	v_mov_b32_e32 v23, 0
	v_mov_b32_e32 v22, 0
	v_mov_b32_e32 v21, 0
	v_mov_b32_e32 v20, 0
	v_mov_b32_e32 v19, 0
	v_mov_b32_e32 v18, 0
	v_mov_b32_e32 v17, 0
	v_mov_b32_e32 v16, 0
	v_mov_b32_e32 v15, 0
	v_mov_b32_e32 v14, 0
	v_mov_b32_e32 v13, 0
	v_mov_b32_e32 v12, 0
	v_mov_b32_e32 v11, 0
	v_mov_b32_e32 v10, 0
	v_mov_b32_e32 v9, 0
	v_mov_b32_e32 v8, 0
	v_mov_b32_e32 v7, 0
	v_mov_b32_e32 v6, 0
	v_mov_b32_e32 v5, 0
	v_mov_b32_e32 v4, 0
	v_mov_b32_e32 v3, 0
	v_mov_b32_e32 v2, 0
	v_mov_b32_e32 v1, 0
	v_mov_b32_e32 v0, 0
	s_cbranch_vccz .LBB0_4464
	s_cmp_gt_i32 s30, 1
	s_cselect_b32 s1, 0x80, 0
	s_add_u32 s14, s14, s1
	s_addc_u32 s15, s15, 0
	v_lshl_add_u64 v[240:241], s[14:15], 0, v[192:193]
	s_add_u32 s10, s10, s1
	v_lshl_add_u64 v[242:243], s[14:15], 0, v[194:195]
	global_load_dwordx4 v[128:131], v[240:241], off
	global_load_dwordx4 v[132:135], v[242:243], off
	v_lshl_add_u64 v[240:241], s[14:15], 0, v[196:197]
	s_addc_u32 s11, s11, 0
	v_lshl_add_u64 v[242:243], s[14:15], 0, v[198:199]
	global_load_dwordx4 v[140:143], v[240:241], off
	global_load_dwordx4 v[136:139], v[242:243], off
	v_lshl_add_u64 v[240:241], s[10:11], 0, v[192:193]
	v_lshl_add_u64 v[242:243], s[10:11], 0, v[194:195]
	global_load_dwordx4 v[148:151], v[240:241], off
	global_load_dwordx4 v[144:147], v[242:243], off
	v_lshl_add_u64 v[240:241], s[10:11], 0, v[196:197]
	v_lshl_add_u64 v[242:243], s[10:11], 0, v[198:199]
	global_load_dwordx4 v[152:155], v[240:241], off
	global_load_dwordx4 v[156:159], v[242:243], off
	s_and_saveexec_b64 s[18:19], s[2:3]
	s_cbranch_execz .LBB0_4486
	v_or_b32_e32 v0, s0, v208
	v_ashrrev_i32_e32 v1, 31, v0
	v_lshlrev_b64 v[0:1], 6, v[0:1]
	v_lshl_add_u64 v[12:13], s[12:13], 0, v[0:1]
	global_load_dwordx4 v[0:3], v[12:13], off
	global_load_dwordx4 v[4:7], v[12:13], off offset:16
	global_load_dwordx4 v[8:11], v[12:13], off offset:32
	s_nop 0
	global_load_dwordx4 v[12:15], v[12:13], off offset:48
	s_waitcnt vmcnt(3)
	v_mov_b32_e32 v16, v1
	v_mov_b32_e32 v17, v2
	s_waitcnt vmcnt(2)
	v_mov_b32_e32 v18, v5
	v_mov_b32_e32 v19, v6
	v_mov_b32_e32 v1, v3
	v_mov_b32_e32 v5, v7
	s_waitcnt vmcnt(1)
	v_mov_b32_e32 v2, v9
	v_mov_b32_e32 v6, v11
	v_pk_add_f32 v[0:1], v[16:17], v[0:1]
	v_pk_add_f32 v[4:5], v[18:19], v[4:5]
	v_pk_add_f32 v[2:3], v[8:9], v[2:3]
	v_pk_add_f32 v[6:7], v[10:11], v[6:7]
	v_pk_add_f32 v[0:1], v[0:1], v[0:1] op_sel:[0,1] op_sel_hi:[1,0]
	v_pk_add_f32 v[4:5], v[4:5], v[4:5] op_sel:[0,1] op_sel_hi:[1,0]
	s_waitcnt vmcnt(0)
	v_mov_b32_e32 v3, v14
	v_mov_b32_e32 v7, v15
	v_mov_b32_e32 v1, v12
	v_mov_b32_e32 v5, v13
	v_pk_add_f32 v[2:3], v[2:3], v[6:7]
	v_pk_add_f32 v[0:1], v[0:1], v[4:5]
	s_nop 0
	v_pk_add_f32 v[0:1], v[0:1], v[2:3]
	s_nop 0
	v_add_f32_e32 v0, v0, v1
	v_fmamk_f32 v0, v0, 0x3a800000, v203
	v_mul_f32_e32 v1, 0x4b800000, v0
	v_cmp_gt_f32_e32 vcc, s25, v0
	s_nop 1
	v_cndmask_b32_e32 v0, v0, v1, vcc
	v_rsq_f32_e32 v0, v0
	s_nop 0
	v_mul_f32_e32 v1, 0x45800000, v0
	v_cndmask_b32_e32 v0, v0, v1, vcc
	ds_write_b32 v202, v0
.LBB0_4486:
	s_or_b64 exec, exec, s[18:19]
	v_mul_lo_u32 v0, v204, s26
	v_lshl_add_u32 v204, v210, 1, v0
	v_or_b32_e32 v0, v209, v206
	v_lshlrev_b32_e32 v1, 3, v207
	v_lshl_or_b32 v2, v205, 6, v206
	s_waitcnt vmcnt(8)
	ds_write_b128 v204, v[160:163]
	ds_write_b128 v204, v[180:183] offset:9216
	ds_write_b128 v204, v[184:187] offset:18432
	ds_write_b128 v204, v[188:191] offset:27648
	ds_write_b128 v204, v[164:167] offset:36864
	ds_write_b128 v204, v[168:171] offset:46080
	ds_write_b128 v204, v[172:175] offset:55296
	ds_write_b128 v204, v[176:179] offset:64512
	s_mov_b32 s1, 0
	s_mov_b32 s10, 0
	s_cmp_lt_i32 s30, 3
	v_mul_lo_u32 v176, v0, s26
	v_mul_u32_u24_e32 v177, 0x90, v2
	v_lshlrev_b32_e32 v178, 1, v1
	s_waitcnt lgkmcnt(0)
	s_barrier
	s_cbranch_scc1 .LBB0_4490
	s_add_i32 s1, s30, -2
	s_add_u32 s6, s6, 0x7dbbb00
	s_addc_u32 s7, s7, 0
	v_lshl_add_u64 v[160:161], s[6:7], 0, v[192:193]
	v_lshl_add_u64 v[162:163], s[6:7], 0, v[194:195]
	v_lshl_add_u64 v[164:165], s[6:7], 0, v[196:197]
	v_lshl_add_u64 v[166:167], s[6:7], 0, v[198:199]
	s_add_u32 s6, s8, 0x6d3bb00
	s_addc_u32 s7, s9, 0
	v_mov_b32_e32 v0, 0
	v_lshl_add_u64 v[168:169], s[6:7], 0, v[192:193]
	v_lshl_add_u64 v[170:171], s[6:7], 0, v[194:195]
	v_lshl_add_u64 v[172:173], s[6:7], 0, v[196:197]
	v_lshl_add_u64 v[174:175], s[6:7], 0, v[198:199]
	s_mov_b64 s[6:7], s[90:91]
	v_mov_b32_e32 v1, v0
	v_mov_b32_e32 v2, v0
	v_mov_b32_e32 v3, v0
	v_mov_b32_e32 v4, v0
	v_mov_b32_e32 v5, v0
	v_mov_b32_e32 v6, v0
	v_mov_b32_e32 v7, v0
	v_mov_b32_e32 v8, v0
	v_mov_b32_e32 v9, v0
	v_mov_b32_e32 v10, v0
	v_mov_b32_e32 v11, v0
	v_mov_b32_e32 v12, v0
	v_mov_b32_e32 v13, v0
	v_mov_b32_e32 v14, v0
	v_mov_b32_e32 v15, v0
	v_mov_b32_e32 v16, v0
	v_mov_b32_e32 v17, v0
	v_mov_b32_e32 v18, v0
	v_mov_b32_e32 v19, v0
	v_mov_b32_e32 v20, v0
	v_mov_b32_e32 v21, v0
	v_mov_b32_e32 v22, v0
	v_mov_b32_e32 v23, v0
	v_mov_b32_e32 v24, v0
	v_mov_b32_e32 v25, v0
	v_mov_b32_e32 v26, v0
	v_mov_b32_e32 v27, v0
	v_mov_b32_e32 v28, v0
	v_mov_b32_e32 v29, v0
	v_mov_b32_e32 v30, v0
	v_mov_b32_e32 v31, v0
	v_mov_b32_e32 v80, v0
	v_mov_b32_e32 v81, v0
	v_mov_b32_e32 v82, v0
	v_mov_b32_e32 v83, v0
	v_mov_b32_e32 v84, v0
	v_mov_b32_e32 v85, v0
	v_mov_b32_e32 v86, v0
	v_mov_b32_e32 v87, v0
	v_mov_b32_e32 v88, v0
	v_mov_b32_e32 v89, v0
	v_mov_b32_e32 v90, v0
	v_mov_b32_e32 v91, v0
	v_mov_b32_e32 v92, v0
	v_mov_b32_e32 v93, v0
	v_mov_b32_e32 v94, v0
	v_mov_b32_e32 v95, v0
	v_mov_b32_e32 v64, v0
	v_mov_b32_e32 v65, v0
	v_mov_b32_e32 v66, v0
	v_mov_b32_e32 v67, v0
	v_mov_b32_e32 v68, v0
	v_mov_b32_e32 v69, v0
	v_mov_b32_e32 v70, v0
	v_mov_b32_e32 v71, v0
	v_mov_b32_e32 v72, v0
	v_mov_b32_e32 v73, v0
	v_mov_b32_e32 v74, v0
	v_mov_b32_e32 v75, v0
	v_mov_b32_e32 v76, v0
	v_mov_b32_e32 v77, v0
	v_mov_b32_e32 v78, v0
	v_mov_b32_e32 v79, v0
	v_mov_b32_e32 v32, v0
	v_mov_b32_e32 v33, v0
	v_mov_b32_e32 v34, v0
	v_mov_b32_e32 v35, v0
	v_mov_b32_e32 v36, v0
	v_mov_b32_e32 v37, v0
	v_mov_b32_e32 v38, v0
	v_mov_b32_e32 v39, v0
	v_mov_b32_e32 v40, v0
	v_mov_b32_e32 v41, v0
	v_mov_b32_e32 v42, v0
	v_mov_b32_e32 v43, v0
	v_mov_b32_e32 v44, v0
	v_mov_b32_e32 v45, v0
	v_mov_b32_e32 v46, v0
	v_mov_b32_e32 v47, v0
	v_mov_b32_e32 v48, v0
	v_mov_b32_e32 v49, v0
	v_mov_b32_e32 v50, v0
	v_mov_b32_e32 v51, v0
	v_mov_b32_e32 v52, v0
	v_mov_b32_e32 v53, v0
	v_mov_b32_e32 v54, v0
	v_mov_b32_e32 v55, v0
	v_mov_b32_e32 v56, v0
	v_mov_b32_e32 v57, v0
	v_mov_b32_e32 v58, v0
	v_mov_b32_e32 v59, v0
	v_mov_b32_e32 v60, v0
	v_mov_b32_e32 v61, v0
	v_mov_b32_e32 v62, v0
	v_mov_b32_e32 v63, v0
	v_mov_b32_e32 v112, v0
	v_mov_b32_e32 v113, v0
	v_mov_b32_e32 v114, v0
	v_mov_b32_e32 v115, v0
	v_mov_b32_e32 v116, v0
	v_mov_b32_e32 v117, v0
	v_mov_b32_e32 v118, v0
	v_mov_b32_e32 v119, v0
	v_mov_b32_e32 v120, v0
	v_mov_b32_e32 v121, v0
	v_mov_b32_e32 v122, v0
	v_mov_b32_e32 v123, v0
	v_mov_b32_e32 v124, v0
	v_mov_b32_e32 v125, v0
	v_mov_b32_e32 v126, v0
	v_mov_b32_e32 v127, v0
	v_mov_b32_e32 v96, v0
	v_mov_b32_e32 v97, v0
	v_mov_b32_e32 v98, v0
	v_mov_b32_e32 v99, v0
	v_mov_b32_e32 v100, v0
	v_mov_b32_e32 v101, v0
	v_mov_b32_e32 v102, v0
	v_mov_b32_e32 v103, v0
	v_mov_b32_e32 v104, v0
	v_mov_b32_e32 v105, v0
	v_mov_b32_e32 v106, v0
	v_mov_b32_e32 v107, v0
	v_mov_b32_e32 v108, v0
	v_mov_b32_e32 v109, v0
	v_mov_b32_e32 v110, v0
	v_mov_b32_e32 v111, v0
